# filter_finalize rewritten by hand: all 16 filter-tap loads of a channel issued first (plus one boundary tap), then scale/convert/store per 512-tap block
# baseline (speedup 1.0000x reference)
; __device__ __forceinline__ unsigned cvt_pk_bf16(float lo, float hi) { const f32x2_t v = {lo, hi}; const bf16x2_t b = __builtin_convertvector(v, bf16x2_t); return __builtin_bit_cast(unsigned, b); }
; __device__ void filter_finalize_phase() {
;     ...
;     for (int oc = gw; oc < 1024; oc += nw) {
;         const int o = oc >> 9, c = oc & 511;
;         float ns = norms[16384 + lane * 2048 + o * 512 + c] + norms[16384 + lane * 2048 + (2 + o) * 512 + c];
; #pragma unroll
;         for (int sft = 32; sft >= 1; sft >>= 1) ns += __shfl_xor(ns, sft);
;         const float scale = 1.0f / (ns + 1e-6f);
;         const float* kf = hraw + ((size_t)(0 * 2 + o) * 512 + c) * 2048; const float* kb = hraw + ((size_t)(1 * 2 + o) * 512 + c) * 2048;
;         for (int it = 0; it < 8; ++it) { const int i0 = it * 512 + lane * 8; float v[8];
; #pragma unroll
;             for (int e = 0; e < 8; ++e) { const int d = 2048 - (i0 + e); float x = 0.f; if (d >= 0 && d <= 2047) x = kf[d]; else if (d < 0 && d >= -2047) x = kb[-d]; v[e] = x * scale; }
;             u32x4 w; w.x = cvt_pk_bf16(v[0], v[1]); w.y = cvt_pk_bf16(v[2], v[3]); w.z = cvt_pk_bf16(v[4], v[5]); w.w = cvt_pk_bf16(v[6], v[7]);
;             *(u32x4*)(rv + (size_t)oc * 4096 + i0) = w; }
.LBB0_245:
	s_or_b64 exec, exec, s[22:23]
	global_load_dword v142, v[36:37], off
	v_sub_u32_e32 v66, 0x1fe4, v24
	v_mov_b32_e32 v67, 0
	v_lshl_add_u64 v[58:59], v[36:37], 0, v[66:67]
	s_mov_b32 s98, 0xfffff000
	s_mov_b32 s99, -1
	v_lshl_add_u64 v[60:61], v[58:59], 0, s[98:99]
	v_add_u32_e32 v68, 0x800000, v24
	v_mov_b32_e32 v69, 0
	v_lshl_add_u64 v[62:63], v[36:37], 0, v[68:69]
	s_mov_b32 s98, 0x1000
	s_mov_b32 s99, 0
	v_lshl_add_u64 v[64:65], v[62:63], 0, s[98:99]
	global_load_dwordx4 v[76:79], v[58:59], off
	global_load_dwordx4 v[80:83], v[58:59], off offset:16
	global_load_dwordx4 v[84:87], v[58:59], off offset:-2048
	global_load_dwordx4 v[88:91], v[58:59], off offset:-2032
	global_load_dwordx4 v[92:95], v[60:61], off
	global_load_dwordx4 v[96:99], v[60:61], off offset:16
	global_load_dwordx4 v[100:103], v[60:61], off offset:-2048
	global_load_dwordx4 v[104:107], v[60:61], off offset:-2032
	global_load_dwordx4 v[108:111], v[62:63], off
	global_load_dwordx4 v[112:115], v[62:63], off offset:16
	global_load_dwordx4 v[116:119], v[62:63], off offset:2048
	global_load_dwordx4 v[120:123], v[62:63], off offset:2064
	global_load_dwordx4 v[124:127], v[64:65], off
	global_load_dwordx4 v[128:131], v[64:65], off offset:16
	global_load_dwordx4 v[132:135], v[64:65], off offset:2048
	global_load_dwordx4 v[136:139], v[64:65], off offset:2064
	s_mov_b32 s98, 0xfffff000
	s_mov_b32 s99, -1
	v_lshl_add_u64 v[70:71], v[4:5], 0, s[98:99]
	s_waitcnt lgkmcnt(0)
	v_add_f32_e32 v1, v1, v13
	v_add_f32_e32 v1, 0x358637bd, v1
	v_div_scale_f32 v7, s[100:101], v1, v1, 1.0
	v_rcp_f32_e32 v9, v7
	s_nop 0
	v_fma_f32 v13, -v7, v9, 1.0
	v_div_scale_f32 v11, vcc, 1.0, v1, 1.0
	v_fmac_f32_e32 v9, v13, v9
	v_mul_f32_e32 v13, v11, v9
	v_fma_f32 v15, -v7, v13, v11
	v_fmac_f32_e32 v13, v15, v9
	v_fma_f32 v7, -v7, v13, v11
	v_div_fmas_f32 v7, v7, v9, v13
	v_div_fixup_f32 v32, v7, v1, 1.0
	s_waitcnt vmcnt(14)
	v_cndmask_b32_e64 v83, v83, 0, s[0:1]
	v_mul_f32_e32 v46, v32, v76
	v_mul_f32_e32 v47, v32, v77
	v_mul_f32_e32 v48, v32, v78
	v_mul_f32_e32 v49, v32, v79
	v_mul_f32_e32 v50, v32, v80
	v_mul_f32_e32 v51, v32, v81
	v_mul_f32_e32 v52, v32, v82
	v_mul_f32_e32 v53, v32, v83
	v_cvt_pk_bf16_f32 v54, v53, v52
	v_cvt_pk_bf16_f32 v55, v51, v50
	v_cvt_pk_bf16_f32 v56, v49, v48
	v_cvt_pk_bf16_f32 v57, v47, v46
	global_store_dwordx4 v[70:71], v[54:57], off offset:-3072
	s_waitcnt vmcnt(13)
	v_mul_f32_e32 v46, v32, v84
	v_mul_f32_e32 v47, v32, v85
	v_mul_f32_e32 v48, v32, v86
	v_mul_f32_e32 v49, v32, v87
	v_mul_f32_e32 v50, v32, v88
	v_mul_f32_e32 v51, v32, v89
	v_mul_f32_e32 v52, v32, v90
	v_mul_f32_e32 v53, v32, v91
	v_cvt_pk_bf16_f32 v54, v53, v52
	v_cvt_pk_bf16_f32 v55, v51, v50
	v_cvt_pk_bf16_f32 v56, v49, v48
	v_cvt_pk_bf16_f32 v57, v47, v46
	global_store_dwordx4 v[70:71], v[54:57], off offset:-2048
	s_waitcnt vmcnt(12)
	v_mul_f32_e32 v46, v32, v92
	v_mul_f32_e32 v47, v32, v93
	v_mul_f32_e32 v48, v32, v94
	v_mul_f32_e32 v49, v32, v95
	v_mul_f32_e32 v50, v32, v96
	v_mul_f32_e32 v51, v32, v97
	v_mul_f32_e32 v52, v32, v98
	v_mul_f32_e32 v53, v32, v99
	v_cvt_pk_bf16_f32 v54, v53, v52
	v_cvt_pk_bf16_f32 v55, v51, v50
	v_cvt_pk_bf16_f32 v56, v49, v48
	v_cvt_pk_bf16_f32 v57, v47, v46
	global_store_dwordx4 v[70:71], v[54:57], off offset:-1024
	s_waitcnt vmcnt(11)
	v_mul_f32_e32 v46, v32, v100
	v_mul_f32_e32 v47, v32, v101
	v_mul_f32_e32 v48, v32, v102
	v_mul_f32_e32 v49, v32, v103
	v_mul_f32_e32 v50, v32, v104
	v_mul_f32_e32 v51, v32, v105
	v_mul_f32_e32 v52, v32, v106
	v_mul_f32_e32 v53, v32, v107
	v_cvt_pk_bf16_f32 v54, v53, v52
	v_cvt_pk_bf16_f32 v55, v51, v50
	v_cvt_pk_bf16_f32 v56, v49, v48
	v_cvt_pk_bf16_f32 v57, v47, v46
	global_store_dwordx4 v[70:71], v[54:57], off
	s_waitcnt vmcnt(10)
	v_cndmask_b32_e64 v108, v108, v142, s[0:1]
	v_mul_f32_e32 v46, v32, v108
	v_mul_f32_e32 v47, v32, v109
	v_mul_f32_e32 v48, v32, v110
	v_mul_f32_e32 v49, v32, v111
	v_mul_f32_e32 v50, v32, v112
	v_mul_f32_e32 v51, v32, v113
	v_mul_f32_e32 v52, v32, v114
	v_mul_f32_e32 v53, v32, v115
	v_cvt_pk_bf16_f32 v54, v46, v47
	v_cvt_pk_bf16_f32 v55, v48, v49
	v_cvt_pk_bf16_f32 v56, v50, v51
	v_cvt_pk_bf16_f32 v57, v52, v53
	global_store_dwordx4 v[4:5], v[54:57], off offset:-3072
	s_waitcnt vmcnt(9)
	v_mul_f32_e32 v46, v32, v116
	v_mul_f32_e32 v47, v32, v117
	v_mul_f32_e32 v48, v32, v118
	v_mul_f32_e32 v49, v32, v119
	v_mul_f32_e32 v50, v32, v120
	v_mul_f32_e32 v51, v32, v121
	v_mul_f32_e32 v52, v32, v122
	v_mul_f32_e32 v53, v32, v123
	v_cvt_pk_bf16_f32 v54, v46, v47
	v_cvt_pk_bf16_f32 v55, v48, v49
	v_cvt_pk_bf16_f32 v56, v50, v51
	v_cvt_pk_bf16_f32 v57, v52, v53
	global_store_dwordx4 v[4:5], v[54:57], off offset:-2048
	s_waitcnt vmcnt(8)
	v_mul_f32_e32 v46, v32, v124
	v_mul_f32_e32 v47, v32, v125
	v_mul_f32_e32 v48, v32, v126
	v_mul_f32_e32 v49, v32, v127
	v_mul_f32_e32 v50, v32, v128
	v_mul_f32_e32 v51, v32, v129
	v_mul_f32_e32 v52, v32, v130
	v_mul_f32_e32 v53, v32, v131
	v_cvt_pk_bf16_f32 v54, v46, v47
	v_cvt_pk_bf16_f32 v55, v48, v49
	v_cvt_pk_bf16_f32 v56, v50, v51
	v_cvt_pk_bf16_f32 v57, v52, v53
	global_store_dwordx4 v[4:5], v[54:57], off offset:-1024
	s_waitcnt vmcnt(7)
	v_mul_f32_e32 v46, v32, v132
	v_mul_f32_e32 v47, v32, v133
	v_mul_f32_e32 v48, v32, v134
	v_mul_f32_e32 v49, v32, v135
	v_mul_f32_e32 v50, v32, v136
	v_mul_f32_e32 v51, v32, v137
	v_mul_f32_e32 v52, v32, v138
	v_mul_f32_e32 v53, v32, v139
	v_cvt_pk_bf16_f32 v54, v46, v47
	v_cvt_pk_bf16_f32 v55, v48, v49
	v_cvt_pk_bf16_f32 v56, v50, v51
	v_cvt_pk_bf16_f32 v57, v52, v53
	global_store_dwordx4 v[4:5], v[54:57], off
	v_add_u32_e32 v0, s16, v0
	v_cmp_lt_i32_e32 vcc, s55, v0
	s_or_b64 s[20:21], vcc, s[20:21]
	v_lshl_add_u64 v[4:5], v[4:5], 0, s[18:19]
	s_andn2_b64 exec, exec, s[20:21]
	s_cbranch_execz .LBB0_248
